# accumulator zero-init with 64 v_mov_b64 instead of 128 v_mov_b32 per tile (in-proj, out, ff1, ff2), on top of loop-edge edit
# speedup vs baseline: 1.0038x; 1.0038x over previous
.LBB0_564:
	s_ashr_i32 s51, s50, 31
	s_lshl_b64 s[10:11], s[50:51], 20
	v_readlane_b32 s34, v250, 61
	v_readlane_b32 s35, v250, 62
	s_add_u32 s52, s34, s10
	s_addc_u32 s53, s35, s11
	s_and_b64 s[10:11], s[42:43], exec
	s_cselect_b32 s28, s53, s7
	s_cselect_b32 s34, s52, s6
	s_ashr_i32 s49, s48, 31
	s_lshl_b64 s[10:11], s[48:49], 20
	s_add_u32 s54, s12, s10
	s_addc_u32 s55, s13, s11
	s_and_b64 s[10:11], s[42:43], exec
	s_cselect_b32 s35, s55, s9
	s_cselect_b32 s44, s54, s8
	s_add_u32 s6, s6, 0x80080
	s_addc_u32 s7, s7, 0
	s_add_u32 s45, s8, 0x100
	v_mov_b64_e32 v[4:5], 0
	v_mov_b64_e32 v[6:7], 0
	v_mov_b64_e32 v[8:9], 0
	v_mov_b64_e32 v[10:11], 0
	v_mov_b64_e32 v[12:13], 0
	v_mov_b64_e32 v[14:15], 0
	v_mov_b64_e32 v[16:17], 0
	v_mov_b64_e32 v[18:19], 0
	v_mov_b64_e32 v[20:21], 0
	v_mov_b64_e32 v[22:23], 0
	v_mov_b64_e32 v[24:25], 0
	v_mov_b64_e32 v[26:27], 0
	v_mov_b64_e32 v[28:29], 0
	v_mov_b64_e32 v[30:31], 0
	v_mov_b64_e32 v[32:33], 0
	v_mov_b64_e32 v[34:35], 0
	v_mov_b64_e32 v[36:37], 0
	v_mov_b64_e32 v[38:39], 0
	v_mov_b64_e32 v[40:41], 0
	v_mov_b64_e32 v[42:43], 0
	v_mov_b64_e32 v[44:45], 0
	v_mov_b64_e32 v[46:47], 0
	v_mov_b64_e32 v[48:49], 0
	v_mov_b64_e32 v[50:51], 0
	v_mov_b64_e32 v[52:53], 0
	v_mov_b64_e32 v[54:55], 0
	v_mov_b64_e32 v[56:57], 0
	v_mov_b64_e32 v[58:59], 0
	v_mov_b64_e32 v[60:61], 0
	v_mov_b64_e32 v[62:63], 0
	v_mov_b64_e32 v[64:65], 0
	v_mov_b64_e32 v[66:67], 0
	v_mov_b64_e32 v[68:69], 0
	v_mov_b64_e32 v[70:71], 0
	v_mov_b64_e32 v[72:73], 0
	v_mov_b64_e32 v[74:75], 0
	v_mov_b64_e32 v[76:77], 0
	v_mov_b64_e32 v[78:79], 0
	v_mov_b64_e32 v[80:81], 0
	v_mov_b64_e32 v[82:83], 0
	v_mov_b64_e32 v[84:85], 0
	v_mov_b64_e32 v[86:87], 0
	v_mov_b64_e32 v[88:89], 0
	v_mov_b64_e32 v[90:91], 0
	v_mov_b64_e32 v[92:93], 0
	v_mov_b64_e32 v[94:95], 0
	v_mov_b64_e32 v[96:97], 0
	v_mov_b64_e32 v[98:99], 0
	v_mov_b64_e32 v[100:101], 0
	v_mov_b64_e32 v[102:103], 0
	v_mov_b64_e32 v[104:105], 0
	v_mov_b64_e32 v[106:107], 0
	v_mov_b64_e32 v[108:109], 0
	v_mov_b64_e32 v[110:111], 0
	v_mov_b64_e32 v[112:113], 0
	v_mov_b64_e32 v[114:115], 0
	v_mov_b64_e32 v[116:117], 0
	v_mov_b64_e32 v[118:119], 0
	v_mov_b64_e32 v[120:121], 0
	v_mov_b64_e32 v[122:123], 0
	v_mov_b64_e32 v[124:125], 0
	v_mov_b64_e32 v[126:127], 0
	v_mov_b64_e32 v[128:129], 0
	v_mov_b64_e32 v[130:131], 0
	s_addc_u32 s49, s9, 0
	s_mov_b32 s51, -2
	s_waitcnt lgkmcnt(0)
	s_mov_b64 s[2:3], 0x80

.LBB0_1086:
	s_add_i32 s9, s47, -2
	s_add_u32 s18, s18, 0x80080
	s_addc_u32 s19, s19, 0
	s_add_u32 s15, s20, 0x100
	v_mov_b64_e32 v[4:5], 0
	v_mov_b64_e32 v[6:7], 0
	v_mov_b64_e32 v[8:9], 0
	v_mov_b64_e32 v[10:11], 0
	v_mov_b64_e32 v[12:13], 0
	v_mov_b64_e32 v[14:15], 0
	v_mov_b64_e32 v[16:17], 0
	v_mov_b64_e32 v[18:19], 0
	v_mov_b64_e32 v[20:21], 0
	v_mov_b64_e32 v[22:23], 0
	v_mov_b64_e32 v[24:25], 0
	v_mov_b64_e32 v[26:27], 0
	v_mov_b64_e32 v[28:29], 0
	v_mov_b64_e32 v[30:31], 0
	v_mov_b64_e32 v[32:33], 0
	v_mov_b64_e32 v[34:35], 0
	v_mov_b64_e32 v[36:37], 0
	v_mov_b64_e32 v[38:39], 0
	v_mov_b64_e32 v[40:41], 0
	v_mov_b64_e32 v[42:43], 0
	v_mov_b64_e32 v[44:45], 0
	v_mov_b64_e32 v[46:47], 0
	v_mov_b64_e32 v[48:49], 0
	v_mov_b64_e32 v[50:51], 0
	v_mov_b64_e32 v[52:53], 0
	v_mov_b64_e32 v[54:55], 0
	v_mov_b64_e32 v[56:57], 0
	v_mov_b64_e32 v[58:59], 0
	v_mov_b64_e32 v[60:61], 0
	v_mov_b64_e32 v[62:63], 0
	v_mov_b64_e32 v[64:65], 0
	v_mov_b64_e32 v[66:67], 0
	v_mov_b64_e32 v[68:69], 0
	v_mov_b64_e32 v[70:71], 0
	v_mov_b64_e32 v[72:73], 0
	v_mov_b64_e32 v[74:75], 0
	v_mov_b64_e32 v[76:77], 0
	v_mov_b64_e32 v[78:79], 0
	v_mov_b64_e32 v[80:81], 0
	v_mov_b64_e32 v[82:83], 0
	v_mov_b64_e32 v[84:85], 0
	v_mov_b64_e32 v[86:87], 0
	v_mov_b64_e32 v[88:89], 0
	v_mov_b64_e32 v[90:91], 0
	v_mov_b64_e32 v[92:93], 0
	v_mov_b64_e32 v[94:95], 0
	v_mov_b64_e32 v[96:97], 0
	v_mov_b64_e32 v[98:99], 0
	v_mov_b64_e32 v[100:101], 0
	v_mov_b64_e32 v[102:103], 0
	v_mov_b64_e32 v[104:105], 0
	v_mov_b64_e32 v[106:107], 0
	v_mov_b64_e32 v[108:109], 0
	v_mov_b64_e32 v[110:111], 0
	v_mov_b64_e32 v[112:113], 0
	v_mov_b64_e32 v[114:115], 0
	v_mov_b64_e32 v[116:117], 0
	v_mov_b64_e32 v[118:119], 0
	v_mov_b64_e32 v[120:121], 0
	v_mov_b64_e32 v[122:123], 0
	v_mov_b64_e32 v[124:125], 0
	v_mov_b64_e32 v[126:127], 0
	v_mov_b64_e32 v[128:129], 0
	v_mov_b64_e32 v[130:131], 0
	s_addc_u32 s51, s21, 0
	s_mov_b32 s20, 0
	s_mov_b64 s[2:3], 0x80

.LBB0_1221:
	s_ashr_i32 s13, s12, 31
	s_lshl_b64 s[14:15], s[12:13], 20
	v_readlane_b32 s16, v250, 61
	v_readlane_b32 s17, v250, 62
	s_add_u32 s14, s16, s14
	s_addc_u32 s15, s17, s15
	s_and_b64 s[16:17], s[40:41], exec
	s_cselect_b32 s13, s15, s19
	s_cselect_b32 s49, s14, s18
	s_ashr_i32 s11, s10, 31
	s_lshl_b64 s[16:17], s[10:11], 20
	s_add_u32 s16, s26, s16
	s_addc_u32 s17, s27, s17
	s_and_b64 s[24:25], s[40:41], exec
	s_cselect_b32 s11, s17, s21
	s_cselect_b32 s50, s16, s20
	s_add_u32 s18, s18, 0x80080
	s_addc_u32 s19, s19, 0
	s_add_u32 s51, s20, 0x100
	v_mov_b64_e32 v[4:5], 0
	v_mov_b64_e32 v[6:7], 0
	v_mov_b64_e32 v[8:9], 0
	v_mov_b64_e32 v[10:11], 0
	v_mov_b64_e32 v[12:13], 0
	v_mov_b64_e32 v[14:15], 0
	v_mov_b64_e32 v[16:17], 0
	v_mov_b64_e32 v[18:19], 0
	v_mov_b64_e32 v[20:21], 0
	v_mov_b64_e32 v[22:23], 0
	v_mov_b64_e32 v[24:25], 0
	v_mov_b64_e32 v[26:27], 0
	v_mov_b64_e32 v[28:29], 0
	v_mov_b64_e32 v[30:31], 0
	v_mov_b64_e32 v[32:33], 0
	v_mov_b64_e32 v[34:35], 0
	v_mov_b64_e32 v[36:37], 0
	v_mov_b64_e32 v[38:39], 0
	v_mov_b64_e32 v[40:41], 0
	v_mov_b64_e32 v[42:43], 0
	v_mov_b64_e32 v[44:45], 0
	v_mov_b64_e32 v[46:47], 0
	v_mov_b64_e32 v[48:49], 0
	v_mov_b64_e32 v[50:51], 0
	v_mov_b64_e32 v[52:53], 0
	v_mov_b64_e32 v[54:55], 0
	v_mov_b64_e32 v[56:57], 0
	v_mov_b64_e32 v[58:59], 0
	v_mov_b64_e32 v[60:61], 0
	v_mov_b64_e32 v[62:63], 0
	v_mov_b64_e32 v[64:65], 0
	v_mov_b64_e32 v[66:67], 0
	v_mov_b64_e32 v[68:69], 0
	v_mov_b64_e32 v[70:71], 0
	v_mov_b64_e32 v[72:73], 0
	v_mov_b64_e32 v[74:75], 0
	v_mov_b64_e32 v[76:77], 0
	v_mov_b64_e32 v[78:79], 0
	v_mov_b64_e32 v[80:81], 0
	v_mov_b64_e32 v[82:83], 0
	v_mov_b64_e32 v[84:85], 0
	v_mov_b64_e32 v[86:87], 0
	v_mov_b64_e32 v[88:89], 0
	v_mov_b64_e32 v[90:91], 0
	v_mov_b64_e32 v[92:93], 0
	v_mov_b64_e32 v[94:95], 0
	v_mov_b64_e32 v[96:97], 0
	v_mov_b64_e32 v[98:99], 0
	v_mov_b64_e32 v[100:101], 0
	v_mov_b64_e32 v[102:103], 0
	v_mov_b64_e32 v[104:105], 0
	v_mov_b64_e32 v[106:107], 0
	v_mov_b64_e32 v[108:109], 0
	v_mov_b64_e32 v[110:111], 0
	v_mov_b64_e32 v[112:113], 0
	v_mov_b64_e32 v[114:115], 0
	v_mov_b64_e32 v[116:117], 0
	v_mov_b64_e32 v[118:119], 0
	v_mov_b64_e32 v[120:121], 0
	v_mov_b64_e32 v[122:123], 0
	v_mov_b64_e32 v[124:125], 0
	v_mov_b64_e32 v[126:127], 0
	v_mov_b64_e32 v[128:129], 0
	v_mov_b64_e32 v[130:131], 0
	s_addc_u32 s52, s21, 0
	s_mov_b32 s53, -2
	s_mov_b64 s[2:3], 0x80

.LBB0_1294:
	s_add_i32 s11, s51, -2
	s_add_u32 s20, s20, 0x200080
	s_addc_u32 s21, s21, 0
	s_add_u32 s17, s24, 0x100
	v_mov_b64_e32 v[4:5], 0
	v_mov_b64_e32 v[6:7], 0
	v_mov_b64_e32 v[8:9], 0
	v_mov_b64_e32 v[10:11], 0
	v_mov_b64_e32 v[12:13], 0
	v_mov_b64_e32 v[14:15], 0
	v_mov_b64_e32 v[16:17], 0
	v_mov_b64_e32 v[18:19], 0
	v_mov_b64_e32 v[20:21], 0
	v_mov_b64_e32 v[22:23], 0
	v_mov_b64_e32 v[24:25], 0
	v_mov_b64_e32 v[26:27], 0
	v_mov_b64_e32 v[28:29], 0
	v_mov_b64_e32 v[30:31], 0
	v_mov_b64_e32 v[32:33], 0
	v_mov_b64_e32 v[34:35], 0
	v_mov_b64_e32 v[36:37], 0
	v_mov_b64_e32 v[38:39], 0
	v_mov_b64_e32 v[40:41], 0
	v_mov_b64_e32 v[42:43], 0
	v_mov_b64_e32 v[44:45], 0
	v_mov_b64_e32 v[46:47], 0
	v_mov_b64_e32 v[48:49], 0
	v_mov_b64_e32 v[50:51], 0
	v_mov_b64_e32 v[52:53], 0
	v_mov_b64_e32 v[54:55], 0
	v_mov_b64_e32 v[56:57], 0
	v_mov_b64_e32 v[58:59], 0
	v_mov_b64_e32 v[60:61], 0
	v_mov_b64_e32 v[62:63], 0
	v_mov_b64_e32 v[64:65], 0
	v_mov_b64_e32 v[66:67], 0
	v_mov_b64_e32 v[68:69], 0
	v_mov_b64_e32 v[70:71], 0
	v_mov_b64_e32 v[72:73], 0
	v_mov_b64_e32 v[74:75], 0
	v_mov_b64_e32 v[76:77], 0
	v_mov_b64_e32 v[78:79], 0
	v_mov_b64_e32 v[80:81], 0
	v_mov_b64_e32 v[82:83], 0
	v_mov_b64_e32 v[84:85], 0
	v_mov_b64_e32 v[86:87], 0
	v_mov_b64_e32 v[88:89], 0
	v_mov_b64_e32 v[90:91], 0
	v_mov_b64_e32 v[92:93], 0
	v_mov_b64_e32 v[94:95], 0
	v_mov_b64_e32 v[96:97], 0
	v_mov_b64_e32 v[98:99], 0
	v_mov_b64_e32 v[100:101], 0
	v_mov_b64_e32 v[102:103], 0
	v_mov_b64_e32 v[104:105], 0
	v_mov_b64_e32 v[106:107], 0
	v_mov_b64_e32 v[108:109], 0
	v_mov_b64_e32 v[110:111], 0
	v_mov_b64_e32 v[112:113], 0
	v_mov_b64_e32 v[114:115], 0
	v_mov_b64_e32 v[116:117], 0
	v_mov_b64_e32 v[118:119], 0
	v_mov_b64_e32 v[120:121], 0
	v_mov_b64_e32 v[122:123], 0
	v_mov_b64_e32 v[124:125], 0
	v_mov_b64_e32 v[126:127], 0
	v_mov_b64_e32 v[128:129], 0
	v_mov_b64_e32 v[130:131], 0
	s_addc_u32 s53, s25, 0
	s_mov_b32 s24, 0
	s_mov_b64 s[2:3], 0x80
